# attention LDS tiles: row stride 272->288 B (conflict-free ds_read_b128 K reads and ds_read_b64_tr V reads); bias-table last-entry load restricted to lane 0
# baseline (speedup 1.0000x reference)
; #define LAS __attribute__((address_space(3)))
; __device__ __forceinline__ void attn_wg_item(const Params& p, int item, LAS unsigned char* lds) {
;   const int tid = threadIdx.x, lane = tid & 63, w = __builtin_amdgcn_readfirstlane(tid >> 6), l15 = lane & 15, kq = lane >> 4;
;   const int hh = w >> 2, qt = w & 3;
;   const bf16_t* PROJ = (const bf16_t*)(p.ws + WS_PROJ); const bf16_t* KVS = (const bf16_t*)(p.ws + WS_KVS); bf16_t* MIX = (bf16_t*)(p.ws + WS_MIX);
;   int h0, qrow, qi, p0, D0, rmin; const bf16_t* Kg; const bf16_t* Vg; size_t ld; bool samp;
;   if (item < 2048) { const int hp = item & 3, c = (item >> 2) & 63, b = item >> 8; samp = false; h0 = 2 * hp;
;     qrow = b * 4096 + c * 64 + qt * 16 + l15; qi = qt * 16 + l15; p0 = c >= 8 ? 0 : 8 - c; D0 = 512; rmin = 0; ld = 4096;
;     Kg = PROJ + ((long)(b * 4096 + c * 64 - 512)) * 4096 + 1024 + h0 * 128; Vg = Kg + 1024; }
;   else { const int s = item - 2048, hp = s & 3, b = s >> 2; samp = true; h0 = 2 * hp;
;     qrow = NPR + b * 16 + l15; qi = l15; p0 = 0; D0 = 560; rmin = 48; ld = 1024;
;     Kg = KVS + (size_t)b * 576 * 1024 + h0 * 128; Vg = Kg + (size_t)16 * 576 * 1024; }
;   const int h = h0 + hh;
;   LAS float* bl = (LAS float*)(lds + 2 * ATT_BUF + hh * 1536);
;   if (qt == 0) { const float* rb = p.in[14] + h * 513; for (int i = lane; i < 321; i += 64) bl[i] = rb[192 + i] * 1.4426950408889634f; }
;   bf16x8 Qf[4];
; #pragma unroll
;   for (int j = 0; j < 4; ++j) Qf[j] = *(const bf16x8*)(PROJ + (size_t)qrow * 4096 + h * 128 + 32 * j + 8 * kq);
;   const int row_s = tid >> 4, chs = tid & 15;
;   const bf16_t* kg0 = Kg + (size_t)row_s * ld + chs * 8; const bf16_t* vg0 = Vg + (size_t)row_s * ld + chs * 8;
;   LAS unsigned char* st0 = lds + row_s * 272 + chs * 16;
.LBB0_790:
	v_lshrrev_b32_e32 v1, 4, v179
	s_add_u32 s56, s88, 0x17264c00
	v_readlane_b32 s36, v247, 1
	s_addc_u32 s57, s89, 0
	v_lshlrev_b32_e32 v0, 3, v1
	v_mov_b32_e32 v97, 0
	v_lshlrev_b32_e32 v98, 2, v1
	v_lshrrev_b32_e32 v1, 2, v99
	v_lshlrev_b32_e32 v96, 2, v144
	v_readlane_b32 s48, v247, 13
	v_readlane_b32 s49, v247, 14
	v_or_b32_e32 v1, v98, v1
	s_add_u32 s96, s88, 0x3e814c00
	v_lshl_add_u64 v[4:5], s[48:49], 0, v[96:97]
	s_mov_b64 s[2:3], 0x300
	v_mbcnt_hi_u32_b32 v149, -1, v149
	v_lshlrev_b32_e32 v2, 3, v99
	v_mul_u32_u24_e32 v3, 0x120, v178
	v_mul_u32_u24_e32 v139, 0x120, v1
	s_addc_u32 s97, s89, 0
	v_lshl_add_u32 v1, v179, 2, 0
	v_lshl_add_u64 v[100:101], v[4:5], 0, s[2:3]
	v_lshlrev_b32_e32 v102, 4, v145
	s_add_i32 s3, 0, 0x24c00
	v_lshlrev_b32_e32 v106, 1, v0
	v_and_b32_e32 v0, 64, v149
	v_readlane_b32 s92, v247, 36
	v_readlane_b32 s94, v247, 57
	v_readlane_b32 s20, v247, 59
	v_readlane_b32 s24, v246, 27
	v_readlane_b32 s80, v246, 25
	s_mov_b32 s1, 0
	v_add3_u32 v137, 0, v3, v70
	v_and_b32_e32 v138, 48, v148
	v_and_b32_e32 v140, 24, v152
	v_mul_u32_u24_e32 v141, 0x120, v99
	v_cmp_gt_u32_e64 s[12:13], 16, v179
	v_subrev_u32_e32 v142, 64, v179
	v_add_u32_e32 v143, 0x24000, v1
	v_sub_u32_e32 v144, 0, v98
	v_mov_b32_e32 v103, v97
	s_movk_i32 s2, 0x100
	v_or_b32_e32 v104, 0x100, v102
	v_mov_b32_e32 v105, v97
	v_mov_b32_e32 v145, s3
	s_movk_i32 s22, 0x83f
	s_mov_b64 s[4:5], 0x100
	v_lshlrev_b32_e32 v108, 1, v2
	s_movk_i32 s23, 0xff
	v_lshlrev_b32_e32 v110, 1, v98
	v_xor_b32_e32 v181, 16, v149
	v_add_u32_e32 v180, 64, v0
	v_xor_b32_e32 v182, 32, v149
	v_mov_b32_e32 v146, 0xf149f2ca
	v_readlane_b32 s93, v247, 37
	v_readlane_b32 s95, v247, 58
	v_readlane_b32 s21, v247, 60
	v_readlane_b32 s25, v246, 28
	v_readlane_b32 s81, v246, 26
	v_readlane_b32 s37, v247, 2
	v_readlane_b32 s38, v247, 3
	v_readlane_b32 s39, v247, 4
	v_readlane_b32 s40, v247, 5
	v_readlane_b32 s41, v247, 6
	v_readlane_b32 s42, v247, 7
	v_readlane_b32 s43, v247, 8
	v_readlane_b32 s44, v247, 9
	v_readlane_b32 s45, v247, 10
	v_readlane_b32 s46, v247, 11
	v_readlane_b32 s47, v247, 12
	v_readlane_b32 s50, v247, 15
	v_readlane_b32 s51, v247, 16
	s_branch .LBB0_794

; #define LAS __attribute__((address_space(3)))
; #define ATT_LOAD(ps_) do { _Pragma("unroll") for (int i = 0; i < 8; ++i) { const bf16_t* g_ = (i >> 2) ? vg0 : kg0; \
;     t[i] = *(const u32x4*)(g_ + ((i >> 1) & 1) * 128 + (size_t)((ps_) * 64 + (i & 1) * 32) * ld); } } while (0)
; #define ATT_STORE(buf_) do { _Pragma("unroll") for (int i = 0; i < 8; ++i) \
;     *(LAS u32x4*)(st0 + (buf_) * ATT_BUF + ((i >> 2) * 2 + ((i >> 1) & 1)) * ATT_TILE + (i & 1) * 32 * 272) = t[i]; } while (0)
; __device__ __forceinline__ void attn_wg_item(const Params& p, int item, LAS unsigned char* lds) {
;     ...
;   if (item < 2048) { const int hp = item & 3, c = (item >> 2) & 63, b = item >> 8; samp = false; h0 = 2 * hp;
;     qrow = b * 4096 + c * 64 + qt * 16 + l15; qi = qt * 16 + l15; p0 = c >= 8 ? 0 : 8 - c; D0 = 512; rmin = 0; ld = 4096;
;     Kg = PROJ + ((long)(b * 4096 + c * 64 - 512)) * 4096 + 1024 + h0 * 128; Vg = Kg + 1024; }
;   else { const int s = item - 2048, hp = s & 3, b = s >> 2; samp = true; h0 = 2 * hp;
;     qrow = NPR + b * 16 + l15; qi = l15; p0 = 0; D0 = 560; rmin = 48; ld = 1024;
;     Kg = KVS + (size_t)b * 576 * 1024 + h0 * 128; Vg = Kg + (size_t)16 * 576 * 1024; }
;   const int h = h0 + hh;
;   LAS float* bl = (LAS float*)(lds + 2 * ATT_BUF + hh * 1536);
;   if (qt == 0) { const float* rb = p.in[14] + h * 513; for (int i = lane; i < 321; i += 64) bl[i] = rb[192 + i] * 1.4426950408889634f; }
;   bf16x8 Qf[4];
; #pragma unroll
;   for (int j = 0; j < 4; ++j) Qf[j] = *(const bf16x8*)(PROJ + (size_t)qrow * 4096 + h * 128 + 32 * j + 8 * kq);
;   const int row_s = tid >> 4, chs = tid & 15;
;   const bf16_t* kg0 = Kg + (size_t)row_s * ld + chs * 8; const bf16_t* vg0 = Vg + (size_t)row_s * ld + chs * 8;
;   LAS unsigned char* st0 = lds + row_s * 272 + chs * 16;
;   u32x4 t[8];
;     ...
;   ATT_LOAD(p0); ATT_STORE(p0 & 1);
;   __syncthreads();
;   f32x4 O[8];
; #pragma unroll
;   for (int dt = 0; dt < 8; ++dt) O[dt] = (f32x4){0.f, 0.f, 0.f, 0.f};
.LBB0_812:
	s_lshr_b32 s36, s0, 8
	s_lshl_b32 s0, s40, 1
	s_and_b32 s37, s0, 6
	s_add_i32 s17, s37, s36
	s_cmp_lg_u32 s33, 0
	s_mul_i32 s35, s36, 0x600
	s_cbranch_scc1 .LBB0_816
	s_mul_i32 s0, s17, 0x201
	v_add_u32_e32 v2, s35, v143
	v_lshl_add_u64 v[0:1], s[0:1], 2, v[100:101]
	global_load_dword v4, v[0:1], off
	global_load_dword v5, v[0:1], off offset:256
	global_load_dword v6, v[0:1], off offset:512
	global_load_dword v7, v[0:1], off offset:768
	global_load_dword v8, v[0:1], off offset:1024
	v_cmp_eq_u32_e32 vcc, 0xffffffc0, v142
	s_and_saveexec_b64 s[18:19], vcc
	global_load_dword v9, v[0:1], off offset:1280
	s_waitcnt vmcnt(0)
	v_mul_f32_e32 v9, 0x3fb8aa3b, v9
	ds_write_b32 v2, v9 offset:1280
	s_mov_b64 exec, s[18:19]
	s_waitcnt vmcnt(0)
	v_mul_f32_e32 v4, 0x3fb8aa3b, v4
	v_mul_f32_e32 v5, 0x3fb8aa3b, v5
	v_mul_f32_e32 v6, 0x3fb8aa3b, v6
	v_mul_f32_e32 v7, 0x3fb8aa3b, v7
	v_mul_f32_e32 v8, 0x3fb8aa3b, v8
	ds_write_b32 v2, v4
	ds_write_b32 v2, v5 offset:256
	ds_write_b32 v2, v6 offset:512
	ds_write_b32 v2, v7 offset:768
	ds_write_b32 v2, v8 offset:1024
.LBB0_816:
	s_lshl_b32 s0, s37, 8
	s_add_u32 s18, s10, s0
	s_addc_u32 s19, s11, 0
	v_mul_u32_u24_e32 v0, s16, v178
	s_add_u32 s38, s18, s14
	v_lshlrev_b32_e32 v96, 1, v0
	s_addc_u32 s39, s19, s15
	v_lshl_add_u64 v[0:1], s[18:19], 0, v[96:97]
	s_lshl_b32 s18, s8, 6
	s_or_b32 s0, s18, 32
	v_mov_b32_e32 v109, v97
	v_lshl_add_u64 v[2:3], s[38:39], 0, v[96:97]
	s_mul_hi_u32 s39, s16, s18
	s_mul_i32 s38, s16, s18
	s_mul_hi_u32 s43, s16, s0
	s_mul_i32 s42, s16, s0
	v_lshl_add_u64 v[0:1], v[0:1], 0, v[108:109]
	v_lshl_add_u64 v[24:25], v[2:3], 0, v[108:109]
	s_lshl_b64 s[38:39], s[38:39], 1
	s_lshl_b64 s[42:43], s[42:43], 1
	v_lshl_add_u64 v[4:5], v[0:1], 0, s[38:39]
	v_lshl_add_u64 v[16:17], v[0:1], 0, s[42:43]
	v_lshl_add_u64 v[8:9], v[24:25], 0, s[38:39]
	v_lshl_add_u64 v[30:31], v[24:25], 0, s[42:43]
	v_cmp_lt_i32_e32 vcc, v181, v180
	global_load_dwordx4 v[0:3], v[4:5], off
	s_nop 0
	global_load_dwordx4 v[4:7], v[4:5], off offset:256
	s_nop 0
	global_load_dwordx4 v[12:15], v[8:9], off
	global_load_dwordx4 v[20:23], v[8:9], off offset:256
	s_nop 0
	global_load_dwordx4 v[8:11], v[16:17], off
	s_nop 0
	global_load_dwordx4 v[16:19], v[16:17], off offset:256
	s_nop 0
	global_load_dwordx4 v[24:27], v[30:31], off
	global_load_dwordx4 v[32:35], v[30:31], off offset:256
	v_or_b32_e32 v112, s9, v99
	v_cndmask_b32_e32 v30, v149, v181, vcc
	v_cmp_lt_i32_e32 vcc, v182, v180
	v_ashrrev_i32_e32 v113, 31, v112
	v_lshlrev_b32_e32 v147, 2, v30
	v_cndmask_b32_e32 v31, v149, v182, vcc
	v_lshlrev_b32_e32 v109, 2, v31
	v_lshlrev_b64 v[30:31], 13, v[112:113]
	v_lshl_add_u64 v[30:31], s[58:59], 0, v[30:31]
	s_lshl_b32 s0, s17, 8
	v_mov_b32_e32 v107, v97
	v_lshl_add_u64 v[30:31], v[30:31], 0, s[0:1]
	v_lshl_add_u64 v[30:31], v[30:31], 0, v[106:107]
	global_load_dwordx4 v[40:43], v[30:31], off
	global_load_dwordx4 v[44:47], v[30:31], off offset:64
	global_load_dwordx4 v[48:51], v[30:31], off offset:128
	global_load_dwordx4 v[52:55], v[30:31], off offset:192
	s_add_i32 s37, s35, 0
	s_lshl_b32 s35, s17, 7
	s_add_i32 s37, s37, 0x24000
	s_mul_i32 s38, s36, 0x4800
	s_mov_b32 s9, s1
	s_bitcmp1_b32 s8, 0
	v_add3_u32 v37, v144, v28, s41
	s_cselect_b32 s0, 0x12000, 0
	s_add_i32 s38, s38, 0
	s_add_i32 s39, s18, 0xfffffe00
	s_sub_i32 s41, s41, 63
	s_lshl_b32 s46, s16, 1
	s_lshl_b64 s[42:43], s[8:9], 6
	v_add_u32_e32 v30, s0, v137
	s_add_u32 s0, s42, 64
	v_and_b32_e32 v36, -16, v28
	s_addc_u32 s9, s43, 0
	v_add_u32_e32 v31, s41, v36
	s_mul_hi_u32 s41, s46, s0
	s_and_b32 s40, s40, 3
	s_mul_i32 s9, s46, s9
	s_mul_i32 s0, s46, s0
	s_lshl_b32 s47, s40, 9
	s_add_i32 s41, s41, s9
	s_add_u32 s40, s0, s47
	s_addc_u32 s41, s41, 0
	s_add_u32 s44, s40, s14
	s_addc_u32 s45, s41, s15
	s_lshl_b32 s0, s16, 7
	s_add_u32 s9, s42, 0x60
	v_lshl_add_u64 v[28:29], s[10:11], 0, v[104:105]
	v_subrev_u32_e32 v107, s18, v31
	v_mov_b32_e32 v153, 0
	s_mov_b32 s19, 0
	s_mov_b32 s36, s34
	v_subrev_u32_e32 v111, s18, v37
	v_lshl_add_u64 v[114:115], v[28:29], 0, s[44:45]
	v_lshl_add_u64 v[118:119], v[28:29], 0, s[40:41]
	v_mov_b32_e32 v155, 0xf149f2ca
	v_mov_b32_e32 v151, v98
	v_mov_b32_e32 v28, 0
	v_mov_b32_e32 v29, v153
	v_mov_b32_e32 v36, 0
	v_mov_b32_e32 v37, v153
	v_mov_b32_e32 v38, v153
	v_mov_b32_e32 v39, v153
	v_mov_b32_e32 v56, 0
	s_waitcnt vmcnt(11)
	ds_write_b128 v30, v[0:3]
	s_waitcnt vmcnt(10)
	ds_write_b128 v30, v[4:7] offset:18432
	s_waitcnt vmcnt(9)
	ds_write_b128 v30, v[12:15] offset:36864
	s_waitcnt vmcnt(8)
	ds_write_b128 v30, v[20:23] offset:55296
	s_waitcnt vmcnt(7)
	ds_write_b128 v30, v[8:11] offset:9216
	s_waitcnt vmcnt(6)
	ds_write_b128 v30, v[16:19] offset:27648
	s_waitcnt vmcnt(5)
	ds_write_b128 v30, v[24:27] offset:46080
	s_waitcnt vmcnt(4)
	ds_write_b128 v30, v[32:35] offset:64512
	v_lshl_add_u64 v[30:31], s[10:11], 0, v[102:103]
	s_addc_u32 s10, s43, 0
	s_mul_i32 s10, s46, s10
	s_mul_hi_u32 s11, s46, s9
	s_add_i32 s11, s11, s10
	s_mul_i32 s46, s46, s9
	s_add_u32 s10, s46, s47
	s_addc_u32 s11, s11, 0
	v_lshl_add_u64 v[116:117], v[30:31], 0, s[10:11]
	s_add_u32 s10, s10, s14
	s_addc_u32 s11, s11, s15
	v_lshl_add_u64 v[120:121], v[30:31], 0, s[10:11]
	s_mov_b32 s9, 0
	v_mov_b32_e32 v30, v153
	v_mov_b32_e32 v31, v153
	v_mov_b32_e32 v57, v153
	v_mov_b32_e32 v58, v153
	v_mov_b32_e32 v59, v153
	v_mov_b32_e32 v60, 0
	v_mov_b32_e32 v61, v153
	v_mov_b32_e32 v62, v153
	v_mov_b32_e32 v63, v153
	v_mov_b32_e32 v64, 0
	v_mov_b32_e32 v65, v153
	v_mov_b32_e32 v66, v153
	v_mov_b32_e32 v67, v153
	v_mov_b32_e32 v68, 0
	v_mov_b32_e32 v69, v153
	v_mov_b32_e32 v70, v153
	v_mov_b32_e32 v71, v153
	v_mov_b32_e32 v72, 0
	v_mov_b32_e32 v73, v153
	v_mov_b32_e32 v74, v153
	v_mov_b32_e32 v75, v153
	v_mov_b32_e32 v76, 0
	v_mov_b32_e32 v77, v153
	v_mov_b32_e32 v78, v153
	v_mov_b32_e32 v79, v153
	s_waitcnt vmcnt(0) lgkmcnt(0)
	s_barrier
	s_cmp_lg_u32 s39, s9
	s_cselect_b64 s[10:11], -1, 0
	s_cmp_eq_u32 s39, s9
	s_cbranch_scc1 .LBB0_818

; #define LAS __attribute__((address_space(3)))
; #define MFMA16(a, b, c) __builtin_amdgcn_mfma_f32_16x16x32_bf16((a), (b), (c), 0, 0, 0)
; #define ATT_LOAD(ps_) do { _Pragma("unroll") for (int i = 0; i < 8; ++i) { const bf16_t* g_ = (i >> 2) ? vg0 : kg0; \
;     t[i] = *(const u32x4*)(g_ + ((i >> 1) & 1) * 128 + (size_t)((ps_) * 64 + (i & 1) * 32) * ld); } } while (0)
; __device__ __forceinline__ void attn_wg_item(const Params& p, int item, LAS unsigned char* lds) {
;     ...
;   for (int ps = p0; ps < 9; ++ps) {
;     const int r0 = ps * 64;
;     if (ps < 8) ATT_LOAD(ps + 1);
;     LAS unsigned char* Kl = lds + (ps & 1) * ATT_BUF + hh * ATT_TILE; LAS unsigned char* Vl = Kl + 2 * ATT_TILE;
;     f32x4 S[4];
; #pragma unroll
;     for (int kt = 0; kt < 4; ++kt) { f32x4 a = (f32x4){0.f, 0.f, 0.f, 0.f};
; #pragma unroll
;       for (int j = 0; j < 4; ++j) { const bf16x8 Kf = *(const LAS bf16x8*)(Kl + (16 * kt + l15) * 272 + 64 * j + 16 * kq); a = MFMA16(Kf, Qf[j], a); }
;       S[kt] = a; }
;     float tmax = -1e30f;
;     if (D0 + (qi & ~15) - (r0 + 63) >= 256 && r0 >= rmin) {
;       const float bc = bl[320];
; #pragma unroll
;       for (int kt = 0; kt < 4; ++kt)
; #pragma unroll
;         for (int i = 0; i < 4; ++i) { const float sv = S[kt][i] + bc; S[kt][i] = sv; tmax = fmaxf(tmax, sv); }
.LBB0_818:
	s_add_i32 s14, s18, s19
	s_bitcmp1_b32 s8, 0
	s_cselect_b32 s15, 0x12000, 0
	s_add_i32 s16, s38, s15
	v_add3_u32 v130, s16, v138, v141
	ds_read_b128 v[184:187], v130
	ds_read_b128 v[188:191], v130 offset:4608
	ds_read_b128 v[192:195], v130 offset:9216
	ds_read_b128 v[196:199], v130 offset:13824
	ds_read_b128 v[200:203], v130 offset:64
	ds_read_b128 v[204:207], v130 offset:4672
	ds_read_b128 v[208:211], v130 offset:9280
	ds_read_b128 v[212:215], v130 offset:13888
	ds_read_b128 v[216:219], v130 offset:128
	ds_read_b128 v[220:223], v130 offset:4736
	ds_read_b128 v[224:227], v130 offset:9344
	ds_read_b128 v[228:231], v130 offset:13952
	ds_read_b128 v[232:235], v130 offset:192
	ds_read_b128 v[236:239], v130 offset:4800
	s_cmp_ge_u32 s14, s34
	s_cselect_b64 s[14:15], -1, 0
	s_waitcnt lgkmcnt(13)
	v_mfma_f32_16x16x32_bf16 v[92:95], v[184:187], v[40:43], 0
	ds_read_b128 v[240:243], v130 offset:9408
	s_waitcnt lgkmcnt(13)
	v_mfma_f32_16x16x32_bf16 v[88:91], v[188:191], v[40:43], 0
	ds_read_b128 v[172:175], v130 offset:14016
	s_waitcnt lgkmcnt(13)
	v_mfma_f32_16x16x32_bf16 v[84:87], v[192:195], v[40:43], 0
	s_waitcnt lgkmcnt(12)
	v_mfma_f32_16x16x32_bf16 v[80:83], v[196:199], v[40:43], 0
	s_waitcnt lgkmcnt(11)
	v_mfma_f32_16x16x32_bf16 v[92:95], v[200:203], v[44:47], v[92:95]
	s_waitcnt lgkmcnt(10)
	v_mfma_f32_16x16x32_bf16 v[88:91], v[204:207], v[44:47], v[88:91]
	s_waitcnt lgkmcnt(9)
	v_mfma_f32_16x16x32_bf16 v[84:87], v[208:211], v[44:47], v[84:87]
	s_waitcnt lgkmcnt(8)
	v_mfma_f32_16x16x32_bf16 v[80:83], v[212:215], v[44:47], v[80:83]
	s_waitcnt lgkmcnt(7)
	v_mfma_f32_16x16x32_bf16 v[92:95], v[216:219], v[48:51], v[92:95]
	s_waitcnt lgkmcnt(6)
	v_mfma_f32_16x16x32_bf16 v[88:91], v[220:223], v[48:51], v[88:91]
	s_waitcnt lgkmcnt(5)
	v_mfma_f32_16x16x32_bf16 v[84:87], v[224:227], v[48:51], v[84:87]
	s_waitcnt lgkmcnt(4)
	v_mfma_f32_16x16x32_bf16 v[80:83], v[228:231], v[48:51], v[80:83]
	v_add_u32_e32 v122, s9, v107
	v_cmp_lt_i32_e32 vcc, s23, v122
	s_waitcnt lgkmcnt(3)
	v_mfma_f32_16x16x32_bf16 v[92:95], v[232:235], v[52:55], v[92:95]
	s_waitcnt lgkmcnt(2)
	v_mfma_f32_16x16x32_bf16 v[88:91], v[236:239], v[52:55], v[88:91]
	s_and_b64 s[14:15], s[14:15], vcc
	s_waitcnt lgkmcnt(1)
	v_mfma_f32_16x16x32_bf16 v[84:87], v[240:243], v[52:55], v[84:87]
	s_waitcnt lgkmcnt(0)
	v_mfma_f32_16x16x32_bf16 v[80:83], v[172:175], v[52:55], v[80:83]
	s_nop 7
	s_and_saveexec_b64 s[40:41], s[14:15]
	s_xor_b64 s[14:15], exec, s[40:41]
	s_cbranch_execz .LBB0_820
	v_mov_b32_e32 v122, s37
	ds_read_b32 v136, v122 offset:1280
	s_waitcnt lgkmcnt(0)
	v_pk_add_f32 v[122:123], v[92:93], v[136:137] op_sel_hi:[1,0]
	v_pk_add_f32 v[124:125], v[94:95], v[136:137] op_sel_hi:[1,0]
	v_pk_add_f32 v[130:131], v[84:85], v[136:137] op_sel_hi:[1,0]
	v_max_f32_e32 v84, 0xf149f2ca, v122
	v_pk_add_f32 v[126:127], v[88:89], v[136:137] op_sel_hi:[1,0]
	v_max3_f32 v84, v84, v123, v124
	v_pk_add_f32 v[128:129], v[90:91], v[136:137] op_sel_hi:[1,0]
	v_max3_f32 v84, v84, v125, v126
	v_max3_f32 v84, v84, v127, v128
	v_max3_f32 v84, v84, v129, v130
	v_pk_add_f32 v[132:133], v[86:87], v[136:137] op_sel_hi:[1,0]
	v_pk_add_f32 v[134:135], v[80:81], v[136:137] op_sel_hi:[1,0]
	v_max3_f32 v84, v84, v131, v132
	v_max3_f32 v84, v84, v133, v134
	v_add_f32_e32 v157, v82, v136
	v_max3_f32 v158, v84, v135, v157

; __device__ __forceinline__ unsigned cvt_pk_bf16(float lo, float hi) { unsigned r; asm("v_cvt_pk_bf16_f32 %0, %1, %2" : "=v"(r) : "v"(lo), "v"(hi)); return r; }
; #define LAS __attribute__((address_space(3)))
; #define MFMA16(a, b, c) __builtin_amdgcn_mfma_f32_16x16x32_bf16((a), (b), (c), 0, 0, 0)
; #define ATT_STORE(buf_) do { _Pragma("unroll") for (int i = 0; i < 8; ++i) \
;     *(LAS u32x4*)(st0 + (buf_) * ATT_BUF + ((i >> 2) * 2 + ((i >> 1) & 1)) * ATT_TILE + (i & 1) * 32 * 272) = t[i]; } while (0)
; __device__ __forceinline__ void attn_wg_item(const Params& p, int item, LAS unsigned char* lds) {
;     ...
;     tmax = fmaxf(tmax, __shfl_xor(tmax, 16)); tmax = fmaxf(tmax, __shfl_xor(tmax, 32));
;     const float mnew = fmaxf(mrun, tmax), alpha = __builtin_amdgcn_exp2f(mrun - mnew); mrun = mnew;
;     float psum = 0.f;
; #pragma unroll
;     for (int kt = 0; kt < 4; ++kt)
; #pragma unroll
;       for (int i = 0; i < 4; ++i) { const float e = __builtin_amdgcn_exp2f(S[kt][i] - mnew); S[kt][i] = e; psum += e; }
;     lsum = lsum * alpha + psum;
; #pragma unroll
;     for (int dt = 0; dt < 8; ++dt) O[dt] *= alpha;
;     bf16x8 Pf[2];
; #pragma unroll
;     for (int s2 = 0; s2 < 2; ++s2) { u32x4 wv; wv.x = cvt_pk_bf16(S[2 * s2][0], S[2 * s2][1]); wv.y = cvt_pk_bf16(S[2 * s2][2], S[2 * s2][3]);
;       wv.z = cvt_pk_bf16(S[2 * s2 + 1][0], S[2 * s2 + 1][1]); wv.w = cvt_pk_bf16(S[2 * s2 + 1][2], S[2 * s2 + 1][3]); Pf[s2] = __builtin_bit_cast(bf16x8, wv); }
;     { const int qq = l15 >> 2, pp = l15 & 3; LAS unsigned char* vb = Vl + (4 * kq + qq) * 272 + pp * 8;
; #pragma unroll
;       for (int s2 = 0; s2 < 2; ++s2)
; #pragma unroll
;         for (int dt = 0; dt < 8; ++dt) {
;           const s16x4 lo = __builtin_amdgcn_ds_read_tr16_b64_v4i16((LAS s16x4*)(vb + (32 * s2) * 272 + dt * 32));
;           const s16x4 hi = __builtin_amdgcn_ds_read_tr16_b64_v4i16((LAS s16x4*)(vb + (32 * s2 + 16) * 272 + dt * 32));
;           const bf16x8 Vf = __builtin_shufflevector(lo, hi, 0, 1, 2, 3, 4, 5, 6, 7);
;           O[dt] = MFMA16(Vf, Pf[s2], O[dt]); } }
;     if (ps < 8) ATT_STORE((ps + 1) & 1);
.LBB0_822:
	s_or_b64 exec, exec, s[14:15]
	s_waitcnt lgkmcnt(0)
	s_nop 0
	v_add_f32_e32 v136, v83, v136
	v_max_f32_e32 v80, v158, v158
	v_max_f32_e32 v80, v80, v136
	s_andn2_b64 vcc, exec, s[10:11]
	v_mov_b32_e32 v81, v80
	v_mov_b32_e32 v166, v80
	s_nop 1
	v_permlane16_swap_b32_e32 v81, v166
	v_max_f32_e32 v80, v81, v166
	v_mov_b32_e32 v81, v80
	v_mov_b32_e32 v166, v80
	s_nop 1
	v_permlane32_swap_b32_e32 v81, v166
	v_max3_f32 v81, v155, v81, v166
	v_sub_f32_e32 v80, v155, v81
	v_sub_f32_e32 v83, v123, v81
	v_sub_f32_e32 v123, v136, v81
	v_add3_u32 v136, s16, v139, v140
	v_exp_f32_e32 v80, v80
	v_sub_f32_e32 v88, v128, v81
	v_sub_f32_e32 v89, v129, v81
	v_sub_f32_e32 v90, v130, v81
	v_sub_f32_e32 v91, v131, v81
	v_sub_f32_e32 v92, v132, v81
	v_sub_f32_e32 v93, v133, v81
	v_sub_f32_e32 v94, v134, v81
	v_sub_f32_e32 v95, v135, v81
	ds_read_b64_tr_b16 v[184:185], v136 offset:36864
	ds_read_b64_tr_b16 v[186:187], v136 offset:41472
	ds_read_b64_tr_b16 v[188:189], v136 offset:36896
	ds_read_b64_tr_b16 v[190:191], v136 offset:41504
	ds_read_b64_tr_b16 v[192:193], v136 offset:36928
	ds_read_b64_tr_b16 v[194:195], v136 offset:41536
	ds_read_b64_tr_b16 v[196:197], v136 offset:36960
	ds_read_b64_tr_b16 v[198:199], v136 offset:41568
	ds_read_b64_tr_b16 v[200:201], v136 offset:36992
	ds_read_b64_tr_b16 v[202:203], v136 offset:41600
	ds_read_b64_tr_b16 v[204:205], v136 offset:37024
	ds_read_b64_tr_b16 v[206:207], v136 offset:41632
	ds_read_b64_tr_b16 v[208:209], v136 offset:37056
	ds_read_b64_tr_b16 v[210:211], v136 offset:41664
	v_sub_f32_e32 v82, v122, v81
	v_sub_f32_e32 v84, v124, v81
	v_sub_f32_e32 v85, v125, v81
	v_sub_f32_e32 v86, v126, v81
	v_sub_f32_e32 v87, v127, v81
	v_pk_mul_f32 v[78:79], v[78:79], v[80:81] op_sel_hi:[1,0]
	v_pk_mul_f32 v[76:77], v[76:77], v[80:81] op_sel_hi:[1,0]
	v_pk_mul_f32 v[74:75], v[74:75], v[80:81] op_sel_hi:[1,0]
	v_pk_mul_f32 v[72:73], v[72:73], v[80:81] op_sel_hi:[1,0]
	v_pk_mul_f32 v[70:71], v[70:71], v[80:81] op_sel_hi:[1,0]
	v_pk_mul_f32 v[68:69], v[68:69], v[80:81] op_sel_hi:[1,0]
	v_pk_mul_f32 v[66:67], v[66:67], v[80:81] op_sel_hi:[1,0]
	v_pk_mul_f32 v[64:65], v[64:65], v[80:81] op_sel_hi:[1,0]
	v_exp_f32_e32 v82, v82
	v_exp_f32_e32 v83, v83
	v_exp_f32_e32 v84, v84
	v_exp_f32_e32 v85, v85
	v_exp_f32_e32 v86, v86
	v_exp_f32_e32 v87, v87
	v_exp_f32_e32 v88, v88
	v_exp_f32_e32 v89, v89
	v_cvt_pk_bf16_f32 v124, v82, v83
	v_cvt_pk_bf16_f32 v125, v84, v85
	v_cvt_pk_bf16_f32 v126, v86, v87
	v_cvt_pk_bf16_f32 v127, v88, v89
	v_pk_mul_f32 v[62:63], v[62:63], v[80:81] op_sel_hi:[1,0]
	s_waitcnt lgkmcnt(12)
	v_mfma_f32_16x16x32_bf16 v[76:79], v[184:187], v[124:127], v[76:79]
	ds_read_b64_tr_b16 v[212:213], v136 offset:37088
	ds_read_b64_tr_b16 v[214:215], v136 offset:41696
	v_pk_mul_f32 v[60:61], v[60:61], v[80:81] op_sel_hi:[1,0]
	v_pk_mul_f32 v[58:59], v[58:59], v[80:81] op_sel_hi:[1,0]
	s_waitcnt lgkmcnt(12)
	v_mfma_f32_16x16x32_bf16 v[72:75], v[188:191], v[124:127], v[72:75]
	ds_read_b64_tr_b16 v[216:217], v136 offset:46080
	ds_read_b64_tr_b16 v[218:219], v136 offset:50688
	v_mul_f32_e64 v56, v56, v80
	v_mul_f32_e64 v57, v57, v80
	v_pk_mul_f32 v[38:39], v[38:39], v[80:81] op_sel_hi:[1,0]
	v_pk_mul_f32 v[36:37], v[36:37], v[80:81] op_sel_hi:[1,0]
	s_waitcnt lgkmcnt(12)
	v_mfma_f32_16x16x32_bf16 v[68:71], v[192:195], v[124:127], v[68:71]
	ds_read_b64_tr_b16 v[220:221], v136 offset:46112
	ds_read_b64_tr_b16 v[222:223], v136 offset:50720
	v_mul_f32_e64 v30, v30, v80
	v_mul_f32_e64 v31, v31, v80
	v_pk_mul_f32 v[28:29], v[28:29], v[80:81] op_sel_hi:[1,0]
	v_sub_f32_e32 v122, v157, v81
	s_waitcnt lgkmcnt(12)
	v_mfma_f32_16x16x32_bf16 v[64:67], v[196:199], v[124:127], v[64:67]
	ds_read_b64_tr_b16 v[224:225], v136 offset:46144
	ds_read_b64_tr_b16 v[226:227], v136 offset:50752
	v_exp_f32_e32 v90, v90
	v_exp_f32_e32 v91, v91
	s_waitcnt lgkmcnt(12)
	v_mfma_f32_16x16x32_bf16 v[60:63], v[200:203], v[124:127], v[60:63]
	ds_read_b64_tr_b16 v[228:229], v136 offset:46176
	ds_read_b64_tr_b16 v[230:231], v136 offset:50784
	v_exp_f32_e32 v92, v92
	v_exp_f32_e32 v93, v93
	v_exp_f32_e32 v94, v94
	s_waitcnt lgkmcnt(12)
	v_mfma_f32_16x16x32_bf16 v[56:59], v[204:207], v[124:127], v[56:59]
	ds_read_b64_tr_b16 v[232:233], v136 offset:46208
	ds_read_b64_tr_b16 v[234:235], v136 offset:50816
	v_exp_f32_e32 v95, v95
	v_exp_f32_e32 v122, v122
	s_waitcnt lgkmcnt(12)
	v_mfma_f32_16x16x32_bf16 v[36:39], v[208:211], v[124:127], v[36:39]
	ds_read_b64_tr_b16 v[236:237], v136 offset:46240
	ds_read_b64_tr_b16 v[238:239], v136 offset:50848
	v_exp_f32_e32 v123, v123
	v_cvt_pk_bf16_f32 v128, v90, v91
	v_cvt_pk_bf16_f32 v129, v92, v93
	s_waitcnt lgkmcnt(12)
	v_mfma_f32_16x16x32_bf16 v[28:31], v[212:215], v[124:127], v[28:31]
	ds_read_b64_tr_b16 v[240:241], v136 offset:46272
	ds_read_b64_tr_b16 v[242:243], v136 offset:50880
	v_cvt_pk_bf16_f32 v130, v94, v95
	v_cvt_pk_bf16_f32 v131, v122, v123
	s_nop 1
	s_waitcnt lgkmcnt(12)
	v_mfma_f32_16x16x32_bf16 v[76:79], v[216:219], v[128:131], v[76:79]
	ds_read_b64_tr_b16 v[172:173], v136 offset:46304
	ds_read_b64_tr_b16 v[174:175], v136 offset:50912
	s_waitcnt lgkmcnt(12)
	v_mfma_f32_16x16x32_bf16 v[72:75], v[220:223], v[128:131], v[72:75]
	s_waitcnt lgkmcnt(10)
	v_mfma_f32_16x16x32_bf16 v[68:71], v[224:227], v[128:131], v[68:71]
	s_waitcnt lgkmcnt(8)
	v_mfma_f32_16x16x32_bf16 v[64:67], v[228:231], v[128:131], v[64:67]
	s_waitcnt lgkmcnt(6)
	v_mfma_f32_16x16x32_bf16 v[60:63], v[232:235], v[128:131], v[60:63]
	s_waitcnt lgkmcnt(4)
	v_mfma_f32_16x16x32_bf16 v[56:59], v[236:239], v[128:131], v[56:59]
	s_waitcnt lgkmcnt(2)
	v_mfma_f32_16x16x32_bf16 v[36:39], v[240:243], v[128:131], v[36:39]
	s_waitcnt lgkmcnt(0)
	v_mfma_f32_16x16x32_bf16 v[28:31], v[172:175], v[128:131], v[28:31]
	s_cbranch_vccnz .LBB0_824
	s_andn2_b32 s10, 1, s8
	s_mul_i32 s10, s10, 0x12000
	v_add_u32_e32 v124, s10, v137
	s_waitcnt vmcnt(0)
	ds_write_b128 v124, v[0:3]
	ds_write_b128 v124, v[8:11] offset:9216
	ds_write_b128 v124, v[4:7] offset:18432
	ds_write_b128 v124, v[16:19] offset:27648
	ds_write_b128 v124, v[12:15] offset:36864
	ds_write_b128 v124, v[24:27] offset:46080
	ds_write_b128 v124, v[20:23] offset:55296
	ds_write_b128 v124, v[32:35] offset:64512
